# LRU combine phase rewritten with 16-byte loads/stores, 6 items (18 loads) in flight per thread
# speedup vs baseline: 1.0078x; 1.0075x over previous
; __device__ __forceinline__ u32x2 pk4(f32x4 v) { u32x2 w; w.x = cvt_pk_bf16(v[0], v[1]); w.y = cvt_pk_bf16(v[2], v[3]); return w; }
; #define UNPK(w) (f32x4){__uint_as_float((w).x << 16), __uint_as_float((w).x & 0xffff0000u), __uint_as_float((w).y << 16), __uint_as_float((w).y & 0xffff0000u)}
; #define UNPK(w) (f32x4){__uint_as_float((w).x << 16), __uint_as_float((w).x & 0xffff0000u), __uint_as_float((w).y << 16), __uint_as_float((w).y & 0xffff0000u)}
; __global__ void __launch_bounds__(NTHR, 2) fwd(Args args) {
;     ...
;                 const size_t NIT = (size_t)R * (D / 4);
; #pragma unroll 1
;                 for (size_t i0 = gtid; i0 < NIT; i0 += 4 * NGT) {
;                     u32x2 hf[4], hb[4], gg[4]; size_t o[4];
; #pragma unroll
;                     for (int k = 0; k < 4; ++k) { const size_t i = i0 + k * NGT; o[k] = (i < NIT ? i : i0) * 4;
;                         hf[k] = __builtin_nontemporal_load((const u32x2*)(HF + o[k])); hb[k] = __builtin_nontemporal_load((const u32x2*)(HF + (size_t)R * D + o[k])); gg[k] = __builtin_nontemporal_load((const u32x2*)(GG + o[k])); }
; #pragma unroll
;                     for (int k = 0; k < 4; ++k) { const f32x4 y = UNPK(gg[k]) * (UNPK(hf[k]) + UNPK(hb[k])); *(u32x2*)(YO + o[k]) = pk4(y); } }
.LBB0_1502:
	v_lshlrev_b32_e32 v6, 4, v2
	s_mov_b32 s14, 3
.Lcmb_loop:
	global_load_dwordx4 v[8:11], v6, s[10:11] nt
	global_load_dwordx4 v[12:15], v6, s[12:13] nt
	global_load_dwordx4 v[16:19], v6, s[6:7] nt
	v_mov_b32_e32 v80, v6
	v_add_u32_e32 v6, 0x200000, v6
	global_load_dwordx4 v[20:23], v6, s[10:11] nt
	global_load_dwordx4 v[24:27], v6, s[12:13] nt
	global_load_dwordx4 v[28:31], v6, s[6:7] nt
	v_mov_b32_e32 v81, v6
	v_add_u32_e32 v6, 0x200000, v6
	global_load_dwordx4 v[32:35], v6, s[10:11] nt
	global_load_dwordx4 v[36:39], v6, s[12:13] nt
	global_load_dwordx4 v[40:43], v6, s[6:7] nt
	v_mov_b32_e32 v82, v6
	v_add_u32_e32 v6, 0x200000, v6
	global_load_dwordx4 v[44:47], v6, s[10:11] nt
	global_load_dwordx4 v[48:51], v6, s[12:13] nt
	global_load_dwordx4 v[52:55], v6, s[6:7] nt
	v_mov_b32_e32 v83, v6
	v_add_u32_e32 v6, 0x200000, v6
	global_load_dwordx4 v[56:59], v6, s[10:11] nt
	global_load_dwordx4 v[60:63], v6, s[12:13] nt
	global_load_dwordx4 v[64:67], v6, s[6:7] nt
	v_mov_b32_e32 v84, v6
	v_add_u32_e32 v6, 0x200000, v6
	global_load_dwordx4 v[68:71], v6, s[10:11] nt
	global_load_dwordx4 v[72:75], v6, s[12:13] nt
	global_load_dwordx4 v[76:79], v6, s[6:7] nt
	v_mov_b32_e32 v85, v6
	v_add_u32_e32 v6, 0x200000, v6
	s_waitcnt vmcnt(15)
	v_lshlrev_b32_e32 v86, 16, v8
	v_and_b32_e32 v87, 0xffff0000, v8
	v_lshlrev_b32_e32 v88, 16, v12
	v_and_b32_e32 v89, 0xffff0000, v12
	v_lshlrev_b32_e32 v90, 16, v16
	v_and_b32_e32 v91, 0xffff0000, v16
	v_lshlrev_b32_e32 v92, 16, v9
	v_and_b32_e32 v93, 0xffff0000, v9
	v_lshlrev_b32_e32 v94, 16, v13
	v_and_b32_e32 v95, 0xffff0000, v13
	v_lshlrev_b32_e32 v96, 16, v17
	v_and_b32_e32 v97, 0xffff0000, v17
	v_lshlrev_b32_e32 v98, 16, v10
	v_and_b32_e32 v99, 0xffff0000, v10
	v_lshlrev_b32_e32 v100, 16, v14
	v_and_b32_e32 v101, 0xffff0000, v14
	v_lshlrev_b32_e32 v102, 16, v18
	v_and_b32_e32 v103, 0xffff0000, v18
	v_lshlrev_b32_e32 v104, 16, v11
	v_and_b32_e32 v105, 0xffff0000, v11
	v_lshlrev_b32_e32 v106, 16, v15
	v_and_b32_e32 v107, 0xffff0000, v15
	v_lshlrev_b32_e32 v108, 16, v19
	v_and_b32_e32 v109, 0xffff0000, v19
	v_pk_add_f32 v[86:87], v[86:87], v[88:89]
	v_pk_add_f32 v[92:93], v[92:93], v[94:95]
	v_pk_add_f32 v[98:99], v[98:99], v[100:101]
	v_pk_add_f32 v[104:105], v[104:105], v[106:107]
	v_pk_mul_f32 v[86:87], v[86:87], v[90:91]
	v_pk_mul_f32 v[92:93], v[92:93], v[96:97]
	v_pk_mul_f32 v[98:99], v[98:99], v[102:103]
	v_pk_mul_f32 v[104:105], v[104:105], v[108:109]
	v_cvt_pk_bf16_f32 v8, v86, v87
	v_cvt_pk_bf16_f32 v9, v92, v93
	v_cvt_pk_bf16_f32 v10, v98, v99
	v_cvt_pk_bf16_f32 v11, v104, v105
	global_store_dwordx4 v80, v[8:11], s[8:9]
	s_waitcnt vmcnt(12)
	v_lshlrev_b32_e32 v86, 16, v20
	v_and_b32_e32 v87, 0xffff0000, v20
	v_lshlrev_b32_e32 v88, 16, v24
	v_and_b32_e32 v89, 0xffff0000, v24
	v_lshlrev_b32_e32 v90, 16, v28
	v_and_b32_e32 v91, 0xffff0000, v28
	v_lshlrev_b32_e32 v92, 16, v21
	v_and_b32_e32 v93, 0xffff0000, v21
	v_lshlrev_b32_e32 v94, 16, v25
	v_and_b32_e32 v95, 0xffff0000, v25
	v_lshlrev_b32_e32 v96, 16, v29
	v_and_b32_e32 v97, 0xffff0000, v29
	v_lshlrev_b32_e32 v98, 16, v22
	v_and_b32_e32 v99, 0xffff0000, v22
	v_lshlrev_b32_e32 v100, 16, v26
	v_and_b32_e32 v101, 0xffff0000, v26
	v_lshlrev_b32_e32 v102, 16, v30
	v_and_b32_e32 v103, 0xffff0000, v30
	v_lshlrev_b32_e32 v104, 16, v23
	v_and_b32_e32 v105, 0xffff0000, v23
	v_lshlrev_b32_e32 v106, 16, v27
	v_and_b32_e32 v107, 0xffff0000, v27
	v_lshlrev_b32_e32 v108, 16, v31
	v_and_b32_e32 v109, 0xffff0000, v31
	v_pk_add_f32 v[86:87], v[86:87], v[88:89]
	v_pk_add_f32 v[92:93], v[92:93], v[94:95]
	v_pk_add_f32 v[98:99], v[98:99], v[100:101]
	v_pk_add_f32 v[104:105], v[104:105], v[106:107]
	v_pk_mul_f32 v[86:87], v[86:87], v[90:91]
	v_pk_mul_f32 v[92:93], v[92:93], v[96:97]
	v_pk_mul_f32 v[98:99], v[98:99], v[102:103]
	v_pk_mul_f32 v[104:105], v[104:105], v[108:109]
	v_cvt_pk_bf16_f32 v20, v86, v87
	v_cvt_pk_bf16_f32 v21, v92, v93
	v_cvt_pk_bf16_f32 v22, v98, v99
	v_cvt_pk_bf16_f32 v23, v104, v105
	global_store_dwordx4 v81, v[20:23], s[8:9]
	s_waitcnt vmcnt(9)
	v_lshlrev_b32_e32 v86, 16, v32
	v_and_b32_e32 v87, 0xffff0000, v32
	v_lshlrev_b32_e32 v88, 16, v36
	v_and_b32_e32 v89, 0xffff0000, v36
	v_lshlrev_b32_e32 v90, 16, v40
	v_and_b32_e32 v91, 0xffff0000, v40
	v_lshlrev_b32_e32 v92, 16, v33
	v_and_b32_e32 v93, 0xffff0000, v33
	v_lshlrev_b32_e32 v94, 16, v37
	v_and_b32_e32 v95, 0xffff0000, v37
	v_lshlrev_b32_e32 v96, 16, v41
	v_and_b32_e32 v97, 0xffff0000, v41
	v_lshlrev_b32_e32 v98, 16, v34
	v_and_b32_e32 v99, 0xffff0000, v34
	v_lshlrev_b32_e32 v100, 16, v38
	v_and_b32_e32 v101, 0xffff0000, v38
	v_lshlrev_b32_e32 v102, 16, v42
	v_and_b32_e32 v103, 0xffff0000, v42
	v_lshlrev_b32_e32 v104, 16, v35
	v_and_b32_e32 v105, 0xffff0000, v35
	v_lshlrev_b32_e32 v106, 16, v39
	v_and_b32_e32 v107, 0xffff0000, v39
	v_lshlrev_b32_e32 v108, 16, v43
	v_and_b32_e32 v109, 0xffff0000, v43
	v_pk_add_f32 v[86:87], v[86:87], v[88:89]
	v_pk_add_f32 v[92:93], v[92:93], v[94:95]
	v_pk_add_f32 v[98:99], v[98:99], v[100:101]
	v_pk_add_f32 v[104:105], v[104:105], v[106:107]
	v_pk_mul_f32 v[86:87], v[86:87], v[90:91]
	v_pk_mul_f32 v[92:93], v[92:93], v[96:97]
	v_pk_mul_f32 v[98:99], v[98:99], v[102:103]
	v_pk_mul_f32 v[104:105], v[104:105], v[108:109]
	v_cvt_pk_bf16_f32 v32, v86, v87
	v_cvt_pk_bf16_f32 v33, v92, v93
	v_cvt_pk_bf16_f32 v34, v98, v99
	v_cvt_pk_bf16_f32 v35, v104, v105
	global_store_dwordx4 v82, v[32:35], s[8:9]
	s_waitcnt vmcnt(6)
; __device__ __forceinline__ u32x2 pk4(f32x4 v) { u32x2 w; w.x = cvt_pk_bf16(v[0], v[1]); w.y = cvt_pk_bf16(v[2], v[3]); return w; }
; #define UNPK(w) (f32x4){__uint_as_float((w).x << 16), __uint_as_float((w).x & 0xffff0000u), __uint_as_float((w).y << 16), __uint_as_float((w).y & 0xffff0000u)}
; #define UNPK(w) (f32x4){__uint_as_float((w).x << 16), __uint_as_float((w).x & 0xffff0000u), __uint_as_float((w).y << 16), __uint_as_float((w).y & 0xffff0000u)}
; __global__ void __launch_bounds__(NTHR, 2) fwd(Args args) {
;     ...
;                     for (int k = 0; k < 4; ++k) { const size_t i = i0 + k * NGT; o[k] = (i < NIT ? i : i0) * 4;
;                         hf[k] = __builtin_nontemporal_load((const u32x2*)(HF + o[k])); hb[k] = __builtin_nontemporal_load((const u32x2*)(HF + (size_t)R * D + o[k])); gg[k] = __builtin_nontemporal_load((const u32x2*)(GG + o[k])); }
; #pragma unroll
;                     for (int k = 0; k < 4; ++k) { const f32x4 y = UNPK(gg[k]) * (UNPK(hf[k]) + UNPK(hb[k])); *(u32x2*)(YO + o[k]) = pk4(y); } }
	v_lshlrev_b32_e32 v86, 16, v44
	v_and_b32_e32 v87, 0xffff0000, v44
	v_lshlrev_b32_e32 v88, 16, v48
	v_and_b32_e32 v89, 0xffff0000, v48
	v_lshlrev_b32_e32 v90, 16, v52
	v_and_b32_e32 v91, 0xffff0000, v52
	v_lshlrev_b32_e32 v92, 16, v45
	v_and_b32_e32 v93, 0xffff0000, v45
	v_lshlrev_b32_e32 v94, 16, v49
	v_and_b32_e32 v95, 0xffff0000, v49
	v_lshlrev_b32_e32 v96, 16, v53
	v_and_b32_e32 v97, 0xffff0000, v53
	v_lshlrev_b32_e32 v98, 16, v46
	v_and_b32_e32 v99, 0xffff0000, v46
	v_lshlrev_b32_e32 v100, 16, v50
	v_and_b32_e32 v101, 0xffff0000, v50
	v_lshlrev_b32_e32 v102, 16, v54
	v_and_b32_e32 v103, 0xffff0000, v54
	v_lshlrev_b32_e32 v104, 16, v47
	v_and_b32_e32 v105, 0xffff0000, v47
	v_lshlrev_b32_e32 v106, 16, v51
	v_and_b32_e32 v107, 0xffff0000, v51
	v_lshlrev_b32_e32 v108, 16, v55
	v_and_b32_e32 v109, 0xffff0000, v55
	v_pk_add_f32 v[86:87], v[86:87], v[88:89]
	v_pk_add_f32 v[92:93], v[92:93], v[94:95]
	v_pk_add_f32 v[98:99], v[98:99], v[100:101]
	v_pk_add_f32 v[104:105], v[104:105], v[106:107]
	v_pk_mul_f32 v[86:87], v[86:87], v[90:91]
	v_pk_mul_f32 v[92:93], v[92:93], v[96:97]
	v_pk_mul_f32 v[98:99], v[98:99], v[102:103]
	v_pk_mul_f32 v[104:105], v[104:105], v[108:109]
	v_cvt_pk_bf16_f32 v44, v86, v87
	v_cvt_pk_bf16_f32 v45, v92, v93
	v_cvt_pk_bf16_f32 v46, v98, v99
	v_cvt_pk_bf16_f32 v47, v104, v105
	global_store_dwordx4 v83, v[44:47], s[8:9]
	s_waitcnt vmcnt(3)
	v_lshlrev_b32_e32 v86, 16, v56
	v_and_b32_e32 v87, 0xffff0000, v56
	v_lshlrev_b32_e32 v88, 16, v60
	v_and_b32_e32 v89, 0xffff0000, v60
	v_lshlrev_b32_e32 v90, 16, v64
	v_and_b32_e32 v91, 0xffff0000, v64
	v_lshlrev_b32_e32 v92, 16, v57
	v_and_b32_e32 v93, 0xffff0000, v57
	v_lshlrev_b32_e32 v94, 16, v61
	v_and_b32_e32 v95, 0xffff0000, v61
	v_lshlrev_b32_e32 v96, 16, v65
	v_and_b32_e32 v97, 0xffff0000, v65
	v_lshlrev_b32_e32 v98, 16, v58
	v_and_b32_e32 v99, 0xffff0000, v58
	v_lshlrev_b32_e32 v100, 16, v62
	v_and_b32_e32 v101, 0xffff0000, v62
	v_lshlrev_b32_e32 v102, 16, v66
	v_and_b32_e32 v103, 0xffff0000, v66
	v_lshlrev_b32_e32 v104, 16, v59
	v_and_b32_e32 v105, 0xffff0000, v59
	v_lshlrev_b32_e32 v106, 16, v63
	v_and_b32_e32 v107, 0xffff0000, v63
	v_lshlrev_b32_e32 v108, 16, v67
	v_and_b32_e32 v109, 0xffff0000, v67
	v_pk_add_f32 v[86:87], v[86:87], v[88:89]
	v_pk_add_f32 v[92:93], v[92:93], v[94:95]
	v_pk_add_f32 v[98:99], v[98:99], v[100:101]
	v_pk_add_f32 v[104:105], v[104:105], v[106:107]
	v_pk_mul_f32 v[86:87], v[86:87], v[90:91]
	v_pk_mul_f32 v[92:93], v[92:93], v[96:97]
	v_pk_mul_f32 v[98:99], v[98:99], v[102:103]
	v_pk_mul_f32 v[104:105], v[104:105], v[108:109]
	v_cvt_pk_bf16_f32 v56, v86, v87
	v_cvt_pk_bf16_f32 v57, v92, v93
	v_cvt_pk_bf16_f32 v58, v98, v99
	v_cvt_pk_bf16_f32 v59, v104, v105
	global_store_dwordx4 v84, v[56:59], s[8:9]
	s_waitcnt vmcnt(0)
	v_lshlrev_b32_e32 v86, 16, v68
	v_and_b32_e32 v87, 0xffff0000, v68
	v_lshlrev_b32_e32 v88, 16, v72
	v_and_b32_e32 v89, 0xffff0000, v72
	v_lshlrev_b32_e32 v90, 16, v76
	v_and_b32_e32 v91, 0xffff0000, v76
	v_lshlrev_b32_e32 v92, 16, v69
	v_and_b32_e32 v93, 0xffff0000, v69
	v_lshlrev_b32_e32 v94, 16, v73
	v_and_b32_e32 v95, 0xffff0000, v73
	v_lshlrev_b32_e32 v96, 16, v77
	v_and_b32_e32 v97, 0xffff0000, v77
	v_lshlrev_b32_e32 v98, 16, v70
	v_and_b32_e32 v99, 0xffff0000, v70
	v_lshlrev_b32_e32 v100, 16, v74
	v_and_b32_e32 v101, 0xffff0000, v74
	v_lshlrev_b32_e32 v102, 16, v78
	v_and_b32_e32 v103, 0xffff0000, v78
	v_lshlrev_b32_e32 v104, 16, v71
	v_and_b32_e32 v105, 0xffff0000, v71
	v_lshlrev_b32_e32 v106, 16, v75
	v_and_b32_e32 v107, 0xffff0000, v75
	v_lshlrev_b32_e32 v108, 16, v79
	v_and_b32_e32 v109, 0xffff0000, v79
	v_pk_add_f32 v[86:87], v[86:87], v[88:89]
	v_pk_add_f32 v[92:93], v[92:93], v[94:95]
	v_pk_add_f32 v[98:99], v[98:99], v[100:101]
	v_pk_add_f32 v[104:105], v[104:105], v[106:107]
	v_pk_mul_f32 v[86:87], v[86:87], v[90:91]
	v_pk_mul_f32 v[92:93], v[92:93], v[96:97]
	v_pk_mul_f32 v[98:99], v[98:99], v[102:103]
	v_pk_mul_f32 v[104:105], v[104:105], v[108:109]
	v_cvt_pk_bf16_f32 v68, v86, v87
	v_cvt_pk_bf16_f32 v69, v92, v93
	v_cvt_pk_bf16_f32 v70, v98, v99
	v_cvt_pk_bf16_f32 v71, v104, v105
	global_store_dwordx4 v85, v[68:71], s[8:9]
	s_sub_i32 s14, s14, 1
	s_cmp_lg_u32 s14, 0
	s_cbranch_scc1 .Lcmb_loop
